# mlaproj UKV items rewritten by hand: 128 rows x two n-tiles sharing the CKV tile and its row rstd (computed once per pair), 3-stage LDS ring, batched KF / transposed VT epilogues; 1056 items instead o
# speedup vs baseline: 1.0091x; 1.0091x over previous
.LBB0_315:
	s_cmpk_lt_i32 s24, 0x630
	s_cbranch_scc1 .Lukv_orig
	s_cmpk_gt_i32 s24, 0xe6f
	s_cbranch_scc1 .Lukv_orig
	s_branch .Lukv

.Lukv:
	s_sub_i32 s0, s24, 0x630
	s_cmpk_gt_i32 s0, 0x41f
	s_cbranch_scc1 .LBB0_314
	s_and_b32 s1, s0, 7
	s_lshr_b32 s2, s0, 3
	s_and_b32 s19, s2, 3
	s_lshr_b32 s2, s2, 2
	s_lshl_b32 s2, s2, 3
	s_or_b32 s1, s2, s1
	s_lshl_b32 s25, s1, 7
	s_lshl_b32 s0, s25, 9
	v_readlane_b32 s48, v225, 48
	v_readlane_b32 s49, v225, 49
	s_nop 1
	s_add_u32 s10, s48, 0xcd7c000
	s_addc_u32 s11, s49, 0
	s_add_u32 s10, s10, s0
	s_addc_u32 s11, s11, 0
	s_lshl_b32 s0, s19, 17
	s_add_u32 s12, s59, s0
	v_readlane_b32 s13, v225, 54
	s_addc_u32 s13, s13, 0
	s_add_u32 s12, s12, 0xc80000
	s_addc_u32 s13, s13, 0
	s_add_u32 s14, s12, 0x10000
	s_addc_u32 s15, s13, 0
	s_cmp_lt_u32 s25, 0x8000
	s_cbranch_scc0 .Lukv_ctx
	s_lshr_b32 s26, s25, 13
	s_and_b32 s27, s25, 0x1fff
	s_add_i32 s27, s27, 0x100
	s_branch .Lukv_ri
.Lukv_ctx:
	s_sub_i32 s27, s25, 0x8000
	s_lshr_b32 s26, s27, 8
	s_and_b32 s27, s27, 0xff
.Lukv_ri:
	s_cmp_lt_u32 s19, 2
	s_cbranch_scc0 .Lukv_offv
	s_lshl_b32 s0, s26, 3
	s_lshl_b32 s1, s19, 2
	s_add_i32 s0, s0, s1
	s_mul_i32 s0, s0, 0x2100
	s_add_i32 s0, s0, s27
	s_mul_i32 s18, s0, 0xc0
	s_branch .Lukv_offd
.Lukv_offv:
	s_lshl_b32 s0, s26, 9
	s_lshl_b32 s1, s19, 8
	s_add_i32 s0, s0, s1
	s_sub_i32 s0, s0, 0x200
	s_mul_i32 s0, s0, 0x4200
	s_lshl_b32 s1, s27, 1
	s_add_i32 s18, s0, s1
.Lukv_offd:
	s_movk_i32 s2, 0x1320
	v_lshrrev_b32_e32 v0, 2, v196
	v_and_b32_e32 v0, 12, v0
	v_lshrrev_b32_e64 v0, v0, s2
	v_xor_b32_e32 v0, v0, v196
	v_and_b32_e32 v0, 3, v0
	v_lshlrev_b32_e32 v0, 4, v0
	v_lshrrev_b32_e32 v2, 2, v196
	v_lshl_add_u32 v2, v2, 9, v0
	v_add_u32_e32 v3, 0x8000, v2
	v_and_b32_e32 v213, 15, v196
	v_and_b32_e32 v214, 12, v213
	v_lshrrev_b32_e64 v214, v214, s2
	v_and_b32_e32 v214, 3, v214
	v_bfe_u32 v215, v196, 4, 2
	v_xor_b32_e32 v214, v214, v215
	v_lshlrev_b32_e32 v214, 4, v214
	v_lshl_add_u32 v214, v213, 6, v214
	v_lshrrev_b32_e32 v213, 7, v196
	v_lshl_add_u32 v64, v213, 12, v214
	v_bfe_u32 v213, v196, 6, 1
	v_lshl_add_u32 v65, v213, 12, v214
	v_add_u32_e32 v141, 0xc000, v64
	v_add_u32_e32 v142, 0xc000, v65
	v_readfirstlane_b32 s16, v196
	s_lshl_b32 s16, s16, 4
	s_mov_b32 m0, s16
	s_nop 0
	global_load_lds_dwordx4 v2, s[10:11]
	s_add_i32 m0, s16, 0x1000
	s_nop 0
	global_load_lds_dwordx4 v3, s[10:11]
	s_add_i32 m0, s16, 0x2000
	s_nop 0
	global_load_lds_dwordx4 v2, s[12:13]
	s_add_i32 m0, s16, 0x3000
	s_nop 0
	global_load_lds_dwordx4 v3, s[12:13]
	s_add_i32 m0, s16, 0x4000
	s_nop 0
	global_load_lds_dwordx4 v2, s[14:15]
	s_add_i32 m0, s16, 0x5000
	s_nop 0
	global_load_lds_dwordx4 v3, s[14:15]
	v_add_u32_e32 v2, 64, v2
	v_add_u32_e32 v3, 64, v3
	s_add_i32 m0, s16, 0x6000
	s_nop 0
	global_load_lds_dwordx4 v2, s[10:11]
	s_add_i32 m0, s16, 0x7000
	s_nop 0
	global_load_lds_dwordx4 v3, s[10:11]
	s_add_i32 m0, s16, 0x8000
	s_nop 0
	global_load_lds_dwordx4 v2, s[12:13]
	s_add_i32 m0, s16, 0x9000
	s_nop 0
	global_load_lds_dwordx4 v3, s[12:13]
	s_add_i32 m0, s16, 0xa000
	s_nop 0
	global_load_lds_dwordx4 v2, s[14:15]
	s_add_i32 m0, s16, 0xb000
	s_nop 0
	global_load_lds_dwordx4 v3, s[14:15]
	v_add_u32_e32 v2, 64, v2
	v_add_u32_e32 v3, 64, v3
	v_lshlrev_b32_e32 v213, 8, v196
	global_load_dwordx4 v[4:7], v213, s[10:11]
	global_load_dwordx4 v[8:11], v213, s[10:11] offset:16
	global_load_dwordx4 v[12:15], v213, s[10:11] offset:32
	global_load_dwordx4 v[16:19], v213, s[10:11] offset:48
	global_load_dwordx4 v[20:23], v213, s[10:11] offset:64
	global_load_dwordx4 v[24:27], v213, s[10:11] offset:80
	global_load_dwordx4 v[28:31], v213, s[10:11] offset:96
	global_load_dwordx4 v[32:35], v213, s[10:11] offset:112
	global_load_dwordx4 v[36:39], v213, s[10:11] offset:128
	global_load_dwordx4 v[40:43], v213, s[10:11] offset:144
	global_load_dwordx4 v[44:47], v213, s[10:11] offset:160
	global_load_dwordx4 v[48:51], v213, s[10:11] offset:176
	global_load_dwordx4 v[52:55], v213, s[10:11] offset:192
	global_load_dwordx4 v[56:59], v213, s[10:11] offset:208
	global_load_dwordx4 v[60:63], v213, s[10:11] offset:224
	global_load_dwordx4 v[72:75], v213, s[10:11] offset:240
	v_mov_b32_e32 v71, 0
	s_waitcnt vmcnt(15)
	v_lshlrev_b32_e32 v76, 16, v4
	v_and_b32_e32 v77, 0xffff0000, v4
	v_pk_mul_f32 v[76:77], v[76:77], v[76:77]
	v_and_b32_e32 v79, 0xffff0000, v6
	v_add_f32_e32 v80, v76, v77
	v_and_b32_e32 v78, 0xffff0000, v5
	v_add_f32_e32 v71, v71, v80
	v_lshlrev_b32_e32 v77, 16, v6
	v_lshlrev_b32_e32 v76, 16, v5
	v_pk_mul_f32 v[80:81], v[78:79], v[78:79]
	s_nop 0
	v_pk_fma_f32 v[80:81], v[76:77], v[76:77], v[80:81]
	s_nop 0
	v_add_f32_e32 v71, v71, v80
	v_add_f32_e32 v71, v71, v81
	v_lshlrev_b32_e32 v76, 16, v7
	v_and_b32_e32 v77, 0xffff0000, v7
	v_pk_mul_f32 v[76:77], v[76:77], v[76:77]
	s_nop 0
	v_add_f32_e32 v76, v76, v77
	v_add_f32_e32 v71, v71, v76
	s_waitcnt vmcnt(14)
	v_lshlrev_b32_e32 v76, 16, v8
	v_and_b32_e32 v77, 0xffff0000, v8
	v_pk_mul_f32 v[76:77], v[76:77], v[76:77]
	v_and_b32_e32 v79, 0xffff0000, v10
	v_add_f32_e32 v80, v76, v77
	v_and_b32_e32 v78, 0xffff0000, v9
	v_add_f32_e32 v71, v71, v80
	v_lshlrev_b32_e32 v77, 16, v10
	v_lshlrev_b32_e32 v76, 16, v9
	v_pk_mul_f32 v[80:81], v[78:79], v[78:79]
	s_nop 0
	v_pk_fma_f32 v[80:81], v[76:77], v[76:77], v[80:81]
	s_nop 0
	v_add_f32_e32 v71, v71, v80
	v_add_f32_e32 v71, v71, v81
	v_lshlrev_b32_e32 v76, 16, v11
	v_and_b32_e32 v77, 0xffff0000, v11
	v_pk_mul_f32 v[76:77], v[76:77], v[76:77]
	s_nop 0
	v_add_f32_e32 v76, v76, v77
	v_add_f32_e32 v71, v71, v76
	s_waitcnt vmcnt(13)
	v_lshlrev_b32_e32 v76, 16, v12
	v_and_b32_e32 v77, 0xffff0000, v12
	v_pk_mul_f32 v[76:77], v[76:77], v[76:77]
	v_and_b32_e32 v79, 0xffff0000, v14
	v_add_f32_e32 v80, v76, v77
	v_and_b32_e32 v78, 0xffff0000, v13
	v_add_f32_e32 v71, v71, v80
	v_lshlrev_b32_e32 v77, 16, v14
	v_lshlrev_b32_e32 v76, 16, v13
	v_pk_mul_f32 v[80:81], v[78:79], v[78:79]
	s_nop 0
	v_pk_fma_f32 v[80:81], v[76:77], v[76:77], v[80:81]
	s_nop 0
	v_add_f32_e32 v71, v71, v80
	v_add_f32_e32 v71, v71, v81
	v_lshlrev_b32_e32 v76, 16, v15
	v_and_b32_e32 v77, 0xffff0000, v15
	v_pk_mul_f32 v[76:77], v[76:77], v[76:77]
	s_nop 0
	v_add_f32_e32 v76, v76, v77
	v_add_f32_e32 v71, v71, v76
	s_waitcnt vmcnt(12)
	v_lshlrev_b32_e32 v76, 16, v16
	v_and_b32_e32 v77, 0xffff0000, v16
	v_pk_mul_f32 v[76:77], v[76:77], v[76:77]
	v_and_b32_e32 v79, 0xffff0000, v18
	v_add_f32_e32 v80, v76, v77
	v_and_b32_e32 v78, 0xffff0000, v17
	v_add_f32_e32 v71, v71, v80
	v_lshlrev_b32_e32 v77, 16, v18
	v_lshlrev_b32_e32 v76, 16, v17
	v_pk_mul_f32 v[80:81], v[78:79], v[78:79]
	s_nop 0
	v_pk_fma_f32 v[80:81], v[76:77], v[76:77], v[80:81]
	s_nop 0
	v_add_f32_e32 v71, v71, v80
	v_add_f32_e32 v71, v71, v81
	v_lshlrev_b32_e32 v76, 16, v19
	v_and_b32_e32 v77, 0xffff0000, v19
	v_pk_mul_f32 v[76:77], v[76:77], v[76:77]
	s_nop 0
	v_add_f32_e32 v76, v76, v77
	v_add_f32_e32 v71, v71, v76
	s_waitcnt vmcnt(11)
	v_lshlrev_b32_e32 v76, 16, v20
	v_and_b32_e32 v77, 0xffff0000, v20
	v_pk_mul_f32 v[76:77], v[76:77], v[76:77]
	v_and_b32_e32 v79, 0xffff0000, v22
	v_add_f32_e32 v80, v76, v77
	v_and_b32_e32 v78, 0xffff0000, v21
	v_add_f32_e32 v71, v71, v80
	v_lshlrev_b32_e32 v77, 16, v22
	v_lshlrev_b32_e32 v76, 16, v21
	v_pk_mul_f32 v[80:81], v[78:79], v[78:79]
	s_nop 0
	v_pk_fma_f32 v[80:81], v[76:77], v[76:77], v[80:81]
	s_nop 0
	v_add_f32_e32 v71, v71, v80
	v_add_f32_e32 v71, v71, v81
	v_lshlrev_b32_e32 v76, 16, v23
	v_and_b32_e32 v77, 0xffff0000, v23
	v_pk_mul_f32 v[76:77], v[76:77], v[76:77]
	s_nop 0
	v_add_f32_e32 v76, v76, v77
	v_add_f32_e32 v71, v71, v76
	s_waitcnt vmcnt(10)
	v_lshlrev_b32_e32 v76, 16, v24
	v_and_b32_e32 v77, 0xffff0000, v24
	v_pk_mul_f32 v[76:77], v[76:77], v[76:77]
	v_and_b32_e32 v79, 0xffff0000, v26
	v_add_f32_e32 v80, v76, v77
	v_and_b32_e32 v78, 0xffff0000, v25
	v_add_f32_e32 v71, v71, v80
	v_lshlrev_b32_e32 v77, 16, v26
	v_lshlrev_b32_e32 v76, 16, v25
	v_pk_mul_f32 v[80:81], v[78:79], v[78:79]
	s_nop 0
	v_pk_fma_f32 v[80:81], v[76:77], v[76:77], v[80:81]
	s_nop 0
	v_add_f32_e32 v71, v71, v80
	v_add_f32_e32 v71, v71, v81
	v_lshlrev_b32_e32 v76, 16, v27
	v_and_b32_e32 v77, 0xffff0000, v27
	v_pk_mul_f32 v[76:77], v[76:77], v[76:77]
	s_nop 0
	v_add_f32_e32 v76, v76, v77
	v_add_f32_e32 v71, v71, v76
	s_waitcnt vmcnt(9)
	v_lshlrev_b32_e32 v76, 16, v28
	v_and_b32_e32 v77, 0xffff0000, v28
	v_pk_mul_f32 v[76:77], v[76:77], v[76:77]
	v_and_b32_e32 v79, 0xffff0000, v30
	v_add_f32_e32 v80, v76, v77
	v_and_b32_e32 v78, 0xffff0000, v29
	v_add_f32_e32 v71, v71, v80
	v_lshlrev_b32_e32 v77, 16, v30
	v_lshlrev_b32_e32 v76, 16, v29
	v_pk_mul_f32 v[80:81], v[78:79], v[78:79]
	s_nop 0
	v_pk_fma_f32 v[80:81], v[76:77], v[76:77], v[80:81]
	s_nop 0
	v_add_f32_e32 v71, v71, v80
	v_add_f32_e32 v71, v71, v81
	v_lshlrev_b32_e32 v76, 16, v31
	v_and_b32_e32 v77, 0xffff0000, v31
	v_pk_mul_f32 v[76:77], v[76:77], v[76:77]
	s_nop 0
	v_add_f32_e32 v76, v76, v77
	v_add_f32_e32 v71, v71, v76
	s_waitcnt vmcnt(8)
	v_lshlrev_b32_e32 v76, 16, v32
	v_and_b32_e32 v77, 0xffff0000, v32
	v_pk_mul_f32 v[76:77], v[76:77], v[76:77]
	v_and_b32_e32 v79, 0xffff0000, v34
	v_add_f32_e32 v80, v76, v77
	v_and_b32_e32 v78, 0xffff0000, v33
	v_add_f32_e32 v71, v71, v80
	v_lshlrev_b32_e32 v77, 16, v34
	v_lshlrev_b32_e32 v76, 16, v33
	v_pk_mul_f32 v[80:81], v[78:79], v[78:79]
	s_nop 0
	v_pk_fma_f32 v[80:81], v[76:77], v[76:77], v[80:81]
	s_nop 0
	v_add_f32_e32 v71, v71, v80
	v_add_f32_e32 v71, v71, v81
	v_lshlrev_b32_e32 v76, 16, v35
	v_and_b32_e32 v77, 0xffff0000, v35
	v_pk_mul_f32 v[76:77], v[76:77], v[76:77]
	s_nop 0
	v_add_f32_e32 v76, v76, v77
	v_add_f32_e32 v71, v71, v76
	s_waitcnt vmcnt(7)
	v_lshlrev_b32_e32 v76, 16, v36
	v_and_b32_e32 v77, 0xffff0000, v36
	v_pk_mul_f32 v[76:77], v[76:77], v[76:77]
	v_and_b32_e32 v79, 0xffff0000, v38
	v_add_f32_e32 v80, v76, v77
	v_and_b32_e32 v78, 0xffff0000, v37
	v_add_f32_e32 v71, v71, v80
	v_lshlrev_b32_e32 v77, 16, v38
	v_lshlrev_b32_e32 v76, 16, v37
	v_pk_mul_f32 v[80:81], v[78:79], v[78:79]
	s_nop 0
	v_pk_fma_f32 v[80:81], v[76:77], v[76:77], v[80:81]
	s_nop 0
	v_add_f32_e32 v71, v71, v80
	v_add_f32_e32 v71, v71, v81
	v_lshlrev_b32_e32 v76, 16, v39
	v_and_b32_e32 v77, 0xffff0000, v39
	v_pk_mul_f32 v[76:77], v[76:77], v[76:77]
	s_nop 0
	v_add_f32_e32 v76, v76, v77
	v_add_f32_e32 v71, v71, v76
	s_waitcnt vmcnt(6)
	v_lshlrev_b32_e32 v76, 16, v40
	v_and_b32_e32 v77, 0xffff0000, v40
	v_pk_mul_f32 v[76:77], v[76:77], v[76:77]
	v_and_b32_e32 v79, 0xffff0000, v42
	v_add_f32_e32 v80, v76, v77
	v_and_b32_e32 v78, 0xffff0000, v41
	v_add_f32_e32 v71, v71, v80
	v_lshlrev_b32_e32 v77, 16, v42
	v_lshlrev_b32_e32 v76, 16, v41
	v_pk_mul_f32 v[80:81], v[78:79], v[78:79]
	s_nop 0
	v_pk_fma_f32 v[80:81], v[76:77], v[76:77], v[80:81]
	s_nop 0
	v_add_f32_e32 v71, v71, v80
	v_add_f32_e32 v71, v71, v81
	v_lshlrev_b32_e32 v76, 16, v43
	v_and_b32_e32 v77, 0xffff0000, v43
	v_pk_mul_f32 v[76:77], v[76:77], v[76:77]
	s_nop 0
	v_add_f32_e32 v76, v76, v77
	v_add_f32_e32 v71, v71, v76
	s_waitcnt vmcnt(5)
	v_lshlrev_b32_e32 v76, 16, v44
	v_and_b32_e32 v77, 0xffff0000, v44
	v_pk_mul_f32 v[76:77], v[76:77], v[76:77]
	v_and_b32_e32 v79, 0xffff0000, v46
	v_add_f32_e32 v80, v76, v77
	v_and_b32_e32 v78, 0xffff0000, v45
	v_add_f32_e32 v71, v71, v80
	v_lshlrev_b32_e32 v77, 16, v46
	v_lshlrev_b32_e32 v76, 16, v45
	v_pk_mul_f32 v[80:81], v[78:79], v[78:79]
	s_nop 0
	v_pk_fma_f32 v[80:81], v[76:77], v[76:77], v[80:81]
	s_nop 0
	v_add_f32_e32 v71, v71, v80
	v_add_f32_e32 v71, v71, v81
	v_lshlrev_b32_e32 v76, 16, v47
	v_and_b32_e32 v77, 0xffff0000, v47
	v_pk_mul_f32 v[76:77], v[76:77], v[76:77]
	s_nop 0
	v_add_f32_e32 v76, v76, v77
	v_add_f32_e32 v71, v71, v76
	s_waitcnt vmcnt(4)
	v_lshlrev_b32_e32 v76, 16, v48
	v_and_b32_e32 v77, 0xffff0000, v48
	v_pk_mul_f32 v[76:77], v[76:77], v[76:77]
	v_and_b32_e32 v79, 0xffff0000, v50
	v_add_f32_e32 v80, v76, v77
	v_and_b32_e32 v78, 0xffff0000, v49
	v_add_f32_e32 v71, v71, v80
	v_lshlrev_b32_e32 v77, 16, v50
	v_lshlrev_b32_e32 v76, 16, v49
	v_pk_mul_f32 v[80:81], v[78:79], v[78:79]
	s_nop 0
	v_pk_fma_f32 v[80:81], v[76:77], v[76:77], v[80:81]
	s_nop 0
	v_add_f32_e32 v71, v71, v80
	v_add_f32_e32 v71, v71, v81
	v_lshlrev_b32_e32 v76, 16, v51
	v_and_b32_e32 v77, 0xffff0000, v51
	v_pk_mul_f32 v[76:77], v[76:77], v[76:77]
	s_nop 0
	v_add_f32_e32 v76, v76, v77
	v_add_f32_e32 v71, v71, v76
	s_waitcnt vmcnt(3)
	v_lshlrev_b32_e32 v76, 16, v52
	v_and_b32_e32 v77, 0xffff0000, v52
	v_pk_mul_f32 v[76:77], v[76:77], v[76:77]
	v_and_b32_e32 v79, 0xffff0000, v54
	v_add_f32_e32 v80, v76, v77
	v_and_b32_e32 v78, 0xffff0000, v53
	v_add_f32_e32 v71, v71, v80
	v_lshlrev_b32_e32 v77, 16, v54
	v_lshlrev_b32_e32 v76, 16, v53
	v_pk_mul_f32 v[80:81], v[78:79], v[78:79]
	s_nop 0
	v_pk_fma_f32 v[80:81], v[76:77], v[76:77], v[80:81]
	s_nop 0
	v_add_f32_e32 v71, v71, v80
	v_add_f32_e32 v71, v71, v81
	v_lshlrev_b32_e32 v76, 16, v55
	v_and_b32_e32 v77, 0xffff0000, v55
	v_pk_mul_f32 v[76:77], v[76:77], v[76:77]
	s_nop 0
	v_add_f32_e32 v76, v76, v77
	v_add_f32_e32 v71, v71, v76
	s_waitcnt vmcnt(2)
	v_lshlrev_b32_e32 v76, 16, v56
	v_and_b32_e32 v77, 0xffff0000, v56
	v_pk_mul_f32 v[76:77], v[76:77], v[76:77]
	v_and_b32_e32 v79, 0xffff0000, v58
	v_add_f32_e32 v80, v76, v77
	v_and_b32_e32 v78, 0xffff0000, v57
	v_add_f32_e32 v71, v71, v80
	v_lshlrev_b32_e32 v77, 16, v58
	v_lshlrev_b32_e32 v76, 16, v57
	v_pk_mul_f32 v[80:81], v[78:79], v[78:79]
	s_nop 0
	v_pk_fma_f32 v[80:81], v[76:77], v[76:77], v[80:81]
	s_nop 0
	v_add_f32_e32 v71, v71, v80
	v_add_f32_e32 v71, v71, v81
	v_lshlrev_b32_e32 v76, 16, v59
	v_and_b32_e32 v77, 0xffff0000, v59
	v_pk_mul_f32 v[76:77], v[76:77], v[76:77]
	s_nop 0
	v_add_f32_e32 v76, v76, v77
	v_add_f32_e32 v71, v71, v76
	s_waitcnt vmcnt(1)
	v_lshlrev_b32_e32 v76, 16, v60
	v_and_b32_e32 v77, 0xffff0000, v60
	v_pk_mul_f32 v[76:77], v[76:77], v[76:77]
	v_and_b32_e32 v79, 0xffff0000, v62
	v_add_f32_e32 v80, v76, v77
	v_and_b32_e32 v78, 0xffff0000, v61
	v_add_f32_e32 v71, v71, v80
	v_lshlrev_b32_e32 v77, 16, v62
	v_lshlrev_b32_e32 v76, 16, v61
	v_pk_mul_f32 v[80:81], v[78:79], v[78:79]
	s_nop 0
	v_pk_fma_f32 v[80:81], v[76:77], v[76:77], v[80:81]
	s_nop 0
	v_add_f32_e32 v71, v71, v80
	v_add_f32_e32 v71, v71, v81
	v_lshlrev_b32_e32 v76, 16, v63
	v_and_b32_e32 v77, 0xffff0000, v63
	v_pk_mul_f32 v[76:77], v[76:77], v[76:77]
	s_nop 0
	v_add_f32_e32 v76, v76, v77
	v_add_f32_e32 v71, v71, v76
	s_waitcnt vmcnt(0)
	v_lshlrev_b32_e32 v76, 16, v72
	v_and_b32_e32 v77, 0xffff0000, v72
	v_pk_mul_f32 v[76:77], v[76:77], v[76:77]
	v_and_b32_e32 v79, 0xffff0000, v74
	v_add_f32_e32 v80, v76, v77
	v_and_b32_e32 v78, 0xffff0000, v73
	v_add_f32_e32 v71, v71, v80
	v_lshlrev_b32_e32 v77, 16, v74
	v_lshlrev_b32_e32 v76, 16, v73
	v_pk_mul_f32 v[80:81], v[78:79], v[78:79]
	s_nop 0
	v_pk_fma_f32 v[80:81], v[76:77], v[76:77], v[80:81]
	s_nop 0
	v_add_f32_e32 v71, v71, v80
	v_add_f32_e32 v71, v71, v81
	v_lshlrev_b32_e32 v76, 16, v75
	v_and_b32_e32 v77, 0xffff0000, v75
	v_pk_mul_f32 v[76:77], v[76:77], v[76:77]
	s_nop 0
	v_add_f32_e32 v76, v76, v77
	v_add_f32_e32 v71, v71, v76
	s_nop 1
	v_add_f32_dpp v76, v71, v71 quad_perm:[1,0,3,2] row_mask:0xf bank_mask:0xf
	v_mul_f32_e32 v76, 0x3b800000, v76
	v_add_f32_e32 v76, 0x358637bd, v76
	v_rsq_f32_e32 v76, v76
	v_lshrrev_b32_e32 v77, 1, v196
	v_lshlrev_b32_e32 v77, 2, v77
	v_add_u32_e32 v77, 0x12000, v77
	v_and_b32_e32 v78, 1, v196
	v_cmp_eq_u32_e32 vcc, 0, v78
	s_nop 1
	s_and_saveexec_b64 s[0:1], vcc
	ds_write_b32 v77, v76
	s_or_b64 exec, exec, s[0:1]
	v_mov_b32_e32 v4, 0
	v_mov_b32_e32 v5, 0
	v_mov_b32_e32 v6, 0
	v_mov_b32_e32 v7, 0
	v_mov_b32_e32 v8, 0
	v_mov_b32_e32 v9, 0
	v_mov_b32_e32 v10, 0
	v_mov_b32_e32 v11, 0
	v_mov_b32_e32 v12, 0
	v_mov_b32_e32 v13, 0
	v_mov_b32_e32 v14, 0
	v_mov_b32_e32 v15, 0
	v_mov_b32_e32 v16, 0
	v_mov_b32_e32 v17, 0
	v_mov_b32_e32 v18, 0
	v_mov_b32_e32 v19, 0
	v_mov_b32_e32 v20, 0
	v_mov_b32_e32 v21, 0
	v_mov_b32_e32 v22, 0
	v_mov_b32_e32 v23, 0
	v_mov_b32_e32 v24, 0
	v_mov_b32_e32 v25, 0
	v_mov_b32_e32 v26, 0
	v_mov_b32_e32 v27, 0
	v_mov_b32_e32 v28, 0
	v_mov_b32_e32 v29, 0
	v_mov_b32_e32 v30, 0
	v_mov_b32_e32 v31, 0
	v_mov_b32_e32 v32, 0
	v_mov_b32_e32 v33, 0
	v_mov_b32_e32 v34, 0
	v_mov_b32_e32 v35, 0
	v_mov_b32_e32 v36, 0
	v_mov_b32_e32 v37, 0
	v_mov_b32_e32 v38, 0
	v_mov_b32_e32 v39, 0
	v_mov_b32_e32 v40, 0
	v_mov_b32_e32 v41, 0
	v_mov_b32_e32 v42, 0
	v_mov_b32_e32 v43, 0
	v_mov_b32_e32 v44, 0
	v_mov_b32_e32 v45, 0
	v_mov_b32_e32 v46, 0
	v_mov_b32_e32 v47, 0
	v_mov_b32_e32 v48, 0
	v_mov_b32_e32 v49, 0
	v_mov_b32_e32 v50, 0
	v_mov_b32_e32 v51, 0
	v_mov_b32_e32 v52, 0
	v_mov_b32_e32 v53, 0
	v_mov_b32_e32 v54, 0
	v_mov_b32_e32 v55, 0
	v_mov_b32_e32 v56, 0
	v_mov_b32_e32 v57, 0
	v_mov_b32_e32 v58, 0
	v_mov_b32_e32 v59, 0
	v_mov_b32_e32 v60, 0
	v_mov_b32_e32 v61, 0
	v_mov_b32_e32 v62, 0
	v_mov_b32_e32 v63, 0
	v_mov_b32_e32 v72, 0
	v_mov_b32_e32 v73, 0
	v_mov_b32_e32 v74, 0
	v_mov_b32_e32 v75, 0
	v_mov_b32_e32 v76, 0
	v_mov_b32_e32 v77, 0
	v_mov_b32_e32 v78, 0
	v_mov_b32_e32 v79, 0
	v_mov_b32_e32 v80, 0
	v_mov_b32_e32 v81, 0
	v_mov_b32_e32 v82, 0
	v_mov_b32_e32 v83, 0
	v_mov_b32_e32 v84, 0
	v_mov_b32_e32 v85, 0
	v_mov_b32_e32 v86, 0
	v_mov_b32_e32 v87, 0
	v_mov_b32_e32 v144, 0
	v_mov_b32_e32 v145, 0
	v_mov_b32_e32 v146, 0
	v_mov_b32_e32 v147, 0
	v_mov_b32_e32 v148, 0
	v_mov_b32_e32 v149, 0
	v_mov_b32_e32 v150, 0
	v_mov_b32_e32 v151, 0
	v_mov_b32_e32 v152, 0
	v_mov_b32_e32 v153, 0
	v_mov_b32_e32 v154, 0
	v_mov_b32_e32 v155, 0
	v_mov_b32_e32 v156, 0
	v_mov_b32_e32 v157, 0
	v_mov_b32_e32 v158, 0
	v_mov_b32_e32 v159, 0
	v_mov_b32_e32 v160, 0
	v_mov_b32_e32 v161, 0
	v_mov_b32_e32 v162, 0
	v_mov_b32_e32 v163, 0
	v_mov_b32_e32 v164, 0
	v_mov_b32_e32 v165, 0
	v_mov_b32_e32 v166, 0
	v_mov_b32_e32 v167, 0
	v_mov_b32_e32 v168, 0
	v_mov_b32_e32 v169, 0
	v_mov_b32_e32 v170, 0
	v_mov_b32_e32 v171, 0
	v_mov_b32_e32 v172, 0
	v_mov_b32_e32 v173, 0
	v_mov_b32_e32 v174, 0
	v_mov_b32_e32 v175, 0
	v_mov_b32_e32 v176, 0
	v_mov_b32_e32 v177, 0
	v_mov_b32_e32 v178, 0
	v_mov_b32_e32 v179, 0
	v_mov_b32_e32 v180, 0
	v_mov_b32_e32 v181, 0
	v_mov_b32_e32 v182, 0
	v_mov_b32_e32 v183, 0
	v_mov_b32_e32 v184, 0
	v_mov_b32_e32 v185, 0
	v_mov_b32_e32 v186, 0
	v_mov_b32_e32 v187, 0
	v_mov_b32_e32 v188, 0
	v_mov_b32_e32 v189, 0
	v_mov_b32_e32 v190, 0
	v_mov_b32_e32 v191, 0
	v_mov_b32_e32 v192, 0
	v_mov_b32_e32 v193, 0
	v_mov_b32_e32 v194, 0
	v_mov_b32_e32 v195, 0
	s_cmp_lt_u32 s19, 2
	s_cbranch_scc0 .Lukv_v
	s_mov_b32 s17, 0
	s_mov_b32 s36, 0
	s_mov_b32 s37, 0xc000
.Lukv_loopk:
	s_waitcnt vmcnt(6)
	s_barrier
	s_cmp_lt_u32 s17, 6
	s_cbranch_scc0 .Lukv_nofillk
	s_add_i32 s0, s16, s37
	s_mov_b32 m0, s0
	s_nop 0
	global_load_lds_dwordx4 v2, s[10:11]
	s_add_i32 m0, s0, 0x1000
	s_nop 0
	global_load_lds_dwordx4 v3, s[10:11]
	s_add_i32 m0, s0, 0x2000
	s_nop 0
	global_load_lds_dwordx4 v2, s[12:13]
	s_add_i32 m0, s0, 0x3000
	s_nop 0
	global_load_lds_dwordx4 v3, s[12:13]
	s_add_i32 m0, s0, 0x4000
	s_nop 0
	global_load_lds_dwordx4 v2, s[14:15]
	s_add_i32 m0, s0, 0x5000
	s_nop 0
	global_load_lds_dwordx4 v3, s[14:15]
	v_add_u32_e32 v2, 64, v2
	v_add_u32_e32 v3, 64, v3
.Lukv_nofillk:
	v_add_u32_e32 v220, s36, v64
	v_add_u32_e32 v227, s36, v65
	ds_read_b128 v[216:219], v220
	ds_read_b128 v[228:231], v220 offset:1024
	ds_read_b128 v[232:235], v220 offset:2048
	ds_read_b128 v[236:239], v220 offset:3072
	ds_read_b128 v[240:243], v227 offset:8192
	ds_read_b128 v[244:247], v227 offset:9216
	ds_read_b128 v[248:251], v227 offset:10240
	ds_read_b128 v[252:255], v227 offset:11264
	s_waitcnt lgkmcnt(3)
	v_mfma_f32_16x16x32_bf16 v[4:7], v[240:243], v[216:219], v[4:7]
	v_mfma_f32_16x16x32_bf16 v[20:23], v[240:243], v[228:231], v[20:23]
	v_mfma_f32_16x16x32_bf16 v[36:39], v[240:243], v[232:235], v[36:39]
	v_mfma_f32_16x16x32_bf16 v[52:55], v[240:243], v[236:239], v[52:55]
	ds_read_b128 v[240:243], v227 offset:16384
	s_waitcnt lgkmcnt(3)
	v_mfma_f32_16x16x32_bf16 v[8:11], v[244:247], v[216:219], v[8:11]
	v_mfma_f32_16x16x32_bf16 v[24:27], v[244:247], v[228:231], v[24:27]
	v_mfma_f32_16x16x32_bf16 v[40:43], v[244:247], v[232:235], v[40:43]
	v_mfma_f32_16x16x32_bf16 v[56:59], v[244:247], v[236:239], v[56:59]
	ds_read_b128 v[244:247], v227 offset:17408
	s_waitcnt lgkmcnt(3)
	v_mfma_f32_16x16x32_bf16 v[12:15], v[248:251], v[216:219], v[12:15]
	v_mfma_f32_16x16x32_bf16 v[28:31], v[248:251], v[228:231], v[28:31]
	v_mfma_f32_16x16x32_bf16 v[44:47], v[248:251], v[232:235], v[44:47]
	v_mfma_f32_16x16x32_bf16 v[60:63], v[248:251], v[236:239], v[60:63]
	ds_read_b128 v[248:251], v227 offset:18432
	s_waitcnt lgkmcnt(3)
	v_mfma_f32_16x16x32_bf16 v[16:19], v[252:255], v[216:219], v[16:19]
	v_mfma_f32_16x16x32_bf16 v[32:35], v[252:255], v[228:231], v[32:35]
	v_mfma_f32_16x16x32_bf16 v[48:51], v[252:255], v[232:235], v[48:51]
	v_mfma_f32_16x16x32_bf16 v[72:75], v[252:255], v[236:239], v[72:75]
	ds_read_b128 v[252:255], v227 offset:19456
	s_waitcnt lgkmcnt(3)
	v_mfma_f32_16x16x32_bf16 v[76:79], v[240:243], v[216:219], v[76:79]
	v_mfma_f32_16x16x32_bf16 v[148:151], v[240:243], v[228:231], v[148:151]
	v_mfma_f32_16x16x32_bf16 v[164:167], v[240:243], v[232:235], v[164:167]
	v_mfma_f32_16x16x32_bf16 v[180:183], v[240:243], v[236:239], v[180:183]
	s_waitcnt lgkmcnt(2)
	v_mfma_f32_16x16x32_bf16 v[80:83], v[244:247], v[216:219], v[80:83]
	v_mfma_f32_16x16x32_bf16 v[152:155], v[244:247], v[228:231], v[152:155]
	v_mfma_f32_16x16x32_bf16 v[168:171], v[244:247], v[232:235], v[168:171]
	v_mfma_f32_16x16x32_bf16 v[184:187], v[244:247], v[236:239], v[184:187]
	s_waitcnt lgkmcnt(1)
	v_mfma_f32_16x16x32_bf16 v[84:87], v[248:251], v[216:219], v[84:87]
	v_mfma_f32_16x16x32_bf16 v[156:159], v[248:251], v[228:231], v[156:159]
	v_mfma_f32_16x16x32_bf16 v[172:175], v[248:251], v[232:235], v[172:175]
	v_mfma_f32_16x16x32_bf16 v[188:191], v[248:251], v[236:239], v[188:191]
	s_waitcnt lgkmcnt(0)
	v_mfma_f32_16x16x32_bf16 v[144:147], v[252:255], v[216:219], v[144:147]
	v_mfma_f32_16x16x32_bf16 v[160:163], v[252:255], v[228:231], v[160:163]
	v_mfma_f32_16x16x32_bf16 v[176:179], v[252:255], v[232:235], v[176:179]
	v_mfma_f32_16x16x32_bf16 v[192:195], v[252:255], v[236:239], v[192:195]
	s_add_i32 s36, s36, 0x6000
	s_cmp_eq_u32 s36, 0x12000
	s_cselect_b32 s36, 0, s36
	s_add_i32 s37, s37, 0x6000
	s_cmp_eq_u32 s37, 0x12000
	s_cselect_b32 s37, 0, s37
	s_add_i32 s17, s17, 1
	s_cmp_lt_u32 s17, 7
	s_cbranch_scc1 .Lukv_loopk
	s_waitcnt vmcnt(0)
	s_barrier
	v_add_u32_e32 v220, s36, v64
	v_add_u32_e32 v227, s36, v65
	ds_read_b128 v[216:219], v220
	ds_read_b128 v[228:231], v220 offset:1024
	ds_read_b128 v[232:235], v220 offset:2048
	ds_read_b128 v[236:239], v220 offset:3072
	ds_read_b128 v[240:243], v227 offset:8192
	ds_read_b128 v[244:247], v227 offset:9216
	ds_read_b128 v[248:251], v227 offset:10240
	ds_read_b128 v[252:255], v227 offset:11264
	s_waitcnt lgkmcnt(3)
	v_mfma_f32_16x16x32_bf16 v[4:7], v[240:243], v[216:219], v[4:7]
	v_mfma_f32_16x16x32_bf16 v[20:23], v[240:243], v[228:231], v[20:23]
	v_mfma_f32_16x16x32_bf16 v[36:39], v[240:243], v[232:235], v[36:39]
	v_mfma_f32_16x16x32_bf16 v[52:55], v[240:243], v[236:239], v[52:55]
	ds_read_b128 v[240:243], v227 offset:16384
	s_waitcnt lgkmcnt(3)
	v_mfma_f32_16x16x32_bf16 v[8:11], v[244:247], v[216:219], v[8:11]
	v_mfma_f32_16x16x32_bf16 v[24:27], v[244:247], v[228:231], v[24:27]
	v_mfma_f32_16x16x32_bf16 v[40:43], v[244:247], v[232:235], v[40:43]
	v_mfma_f32_16x16x32_bf16 v[56:59], v[244:247], v[236:239], v[56:59]
	ds_read_b128 v[244:247], v227 offset:17408
	s_waitcnt lgkmcnt(3)
	v_mfma_f32_16x16x32_bf16 v[12:15], v[248:251], v[216:219], v[12:15]
	v_mfma_f32_16x16x32_bf16 v[28:31], v[248:251], v[228:231], v[28:31]
	v_mfma_f32_16x16x32_bf16 v[44:47], v[248:251], v[232:235], v[44:47]
	v_mfma_f32_16x16x32_bf16 v[60:63], v[248:251], v[236:239], v[60:63]
	ds_read_b128 v[248:251], v227 offset:18432
	s_waitcnt lgkmcnt(3)
	v_mfma_f32_16x16x32_bf16 v[16:19], v[252:255], v[216:219], v[16:19]
	v_mfma_f32_16x16x32_bf16 v[32:35], v[252:255], v[228:231], v[32:35]
	v_mfma_f32_16x16x32_bf16 v[48:51], v[252:255], v[232:235], v[48:51]
	v_mfma_f32_16x16x32_bf16 v[72:75], v[252:255], v[236:239], v[72:75]
	ds_read_b128 v[252:255], v227 offset:19456
	s_waitcnt lgkmcnt(3)
	v_mfma_f32_16x16x32_bf16 v[76:79], v[240:243], v[216:219], v[76:79]
	v_mfma_f32_16x16x32_bf16 v[148:151], v[240:243], v[228:231], v[148:151]
	v_mfma_f32_16x16x32_bf16 v[164:167], v[240:243], v[232:235], v[164:167]
	v_mfma_f32_16x16x32_bf16 v[180:183], v[240:243], v[236:239], v[180:183]
	s_waitcnt lgkmcnt(2)
	v_mfma_f32_16x16x32_bf16 v[80:83], v[244:247], v[216:219], v[80:83]
	v_mfma_f32_16x16x32_bf16 v[152:155], v[244:247], v[228:231], v[152:155]
	v_mfma_f32_16x16x32_bf16 v[168:171], v[244:247], v[232:235], v[168:171]
	v_mfma_f32_16x16x32_bf16 v[184:187], v[244:247], v[236:239], v[184:187]
	s_waitcnt lgkmcnt(1)
	v_mfma_f32_16x16x32_bf16 v[84:87], v[248:251], v[216:219], v[84:87]
	v_mfma_f32_16x16x32_bf16 v[156:159], v[248:251], v[228:231], v[156:159]
	v_mfma_f32_16x16x32_bf16 v[172:175], v[248:251], v[232:235], v[172:175]
	v_mfma_f32_16x16x32_bf16 v[188:191], v[248:251], v[236:239], v[188:191]
	s_waitcnt lgkmcnt(0)
	v_mfma_f32_16x16x32_bf16 v[144:147], v[252:255], v[216:219], v[144:147]
	v_mfma_f32_16x16x32_bf16 v[160:163], v[252:255], v[228:231], v[160:163]
	v_mfma_f32_16x16x32_bf16 v[176:179], v[252:255], v[232:235], v[176:179]
	v_mfma_f32_16x16x32_bf16 v[192:195], v[252:255], v[236:239], v[192:195]
	s_barrier
	v_and_b32_e32 v213, 15, v196
	v_lshrrev_b32_e32 v220, 7, v196
	v_lshl_add_u32 v213, v220, 6, v213
	v_lshl_add_u32 v227, v213, 2, 0
	v_add_u32_e32 v227, 0x12000, v227
	v_mul_u32_u24_e32 v213, 0x110, v213
	v_bfe_u32 v220, v196, 6, 1
	v_lshl_add_u32 v213, v220, 7, v213
	v_bfe_u32 v220, v196, 4, 2
	v_lshl_add_u32 v213, v220, 3, v213
	v_lshrrev_b32_e32 v220, 4, v196
	v_and_b32_e32 v0, 15, v196
	v_and_b32_e32 v71, 7, v0
	v_lshlrev_b32_e32 v71, 4, v71
	v_lshrrev_b32_e32 v143, 3, v0
	s_mov_b32 s0, 0x18c000
	v_mul_lo_u32 v143, v143, s0
	v_add_u32_e32 v71, v71, v143
	s_movk_i32 s0, 0xc0
	v_mad_u32_u24 v71, v220, s0, v71
	v_lshlrev_b32_e32 v0, 4, v0
	v_mad_u32_u24 v143, v220, s30, v0
	s_add_u32 s46, s48, 0x1349c000
	s_addc_u32 s47, s49, 0
	s_add_u32 s46, s46, s18
	s_addc_u32 s47, s47, 0
	ds_read_b32 v216, v227 offset:0
	ds_read_b32 v217, v227 offset:64
	ds_read_b32 v218, v227 offset:128
	ds_read_b32 v219, v227 offset:192
	s_waitcnt lgkmcnt(0)
	v_mul_f32_e32 v4, v4, v216
	v_mul_f32_e32 v5, v5, v216
	v_mul_f32_e32 v6, v6, v216
	v_mul_f32_e32 v7, v7, v216
	v_cvt_pk_bf16_f32 v2, v4, v5
	v_cvt_pk_bf16_f32 v3, v6, v7
	ds_write_b64 v213, v[2:3] offset:0
	v_mul_f32_e32 v8, v8, v216
	v_mul_f32_e32 v9, v9, v216
	v_mul_f32_e32 v10, v10, v216
	v_mul_f32_e32 v11, v11, v216
	v_cvt_pk_bf16_f32 v214, v8, v9
	v_cvt_pk_bf16_f32 v215, v10, v11
	ds_write_b64 v213, v[214:215] offset:32
	v_mul_f32_e32 v12, v12, v216
	v_mul_f32_e32 v13, v13, v216
	v_mul_f32_e32 v14, v14, v216
	v_mul_f32_e32 v15, v15, v216
	v_cvt_pk_bf16_f32 v2, v12, v13
	v_cvt_pk_bf16_f32 v3, v14, v15
	ds_write_b64 v213, v[2:3] offset:64
	v_mul_f32_e32 v16, v16, v216
	v_mul_f32_e32 v17, v17, v216
	v_mul_f32_e32 v18, v18, v216
	v_mul_f32_e32 v19, v19, v216
	v_cvt_pk_bf16_f32 v214, v16, v17
	v_cvt_pk_bf16_f32 v215, v18, v19
	ds_write_b64 v213, v[214:215] offset:96
	v_mul_f32_e32 v20, v20, v217
	v_mul_f32_e32 v21, v21, v217
	v_mul_f32_e32 v22, v22, v217
	v_mul_f32_e32 v23, v23, v217
	v_cvt_pk_bf16_f32 v2, v20, v21
	v_cvt_pk_bf16_f32 v3, v22, v23
	ds_write_b64 v213, v[2:3] offset:4352
	v_mul_f32_e32 v24, v24, v217
	v_mul_f32_e32 v25, v25, v217
	v_mul_f32_e32 v26, v26, v217
	v_mul_f32_e32 v27, v27, v217
	v_cvt_pk_bf16_f32 v214, v24, v25
	v_cvt_pk_bf16_f32 v215, v26, v27
	ds_write_b64 v213, v[214:215] offset:4384
	v_mul_f32_e32 v28, v28, v217
	v_mul_f32_e32 v29, v29, v217
	v_mul_f32_e32 v30, v30, v217
	v_mul_f32_e32 v31, v31, v217
	v_cvt_pk_bf16_f32 v2, v28, v29
	v_cvt_pk_bf16_f32 v3, v30, v31
	ds_write_b64 v213, v[2:3] offset:4416
	v_mul_f32_e32 v32, v32, v217
	v_mul_f32_e32 v33, v33, v217
	v_mul_f32_e32 v34, v34, v217
	v_mul_f32_e32 v35, v35, v217
	v_cvt_pk_bf16_f32 v214, v32, v33
	v_cvt_pk_bf16_f32 v215, v34, v35
	ds_write_b64 v213, v[214:215] offset:4448
	v_mul_f32_e32 v36, v36, v218
	v_mul_f32_e32 v37, v37, v218
	v_mul_f32_e32 v38, v38, v218
	v_mul_f32_e32 v39, v39, v218
	v_cvt_pk_bf16_f32 v2, v36, v37
	v_cvt_pk_bf16_f32 v3, v38, v39
	ds_write_b64 v213, v[2:3] offset:8704
	v_mul_f32_e32 v40, v40, v218
	v_mul_f32_e32 v41, v41, v218
	v_mul_f32_e32 v42, v42, v218
	v_mul_f32_e32 v43, v43, v218
	v_cvt_pk_bf16_f32 v214, v40, v41
	v_cvt_pk_bf16_f32 v215, v42, v43
	ds_write_b64 v213, v[214:215] offset:8736
	v_mul_f32_e32 v44, v44, v218
	v_mul_f32_e32 v45, v45, v218
	v_mul_f32_e32 v46, v46, v218
	v_mul_f32_e32 v47, v47, v218
	v_cvt_pk_bf16_f32 v2, v44, v45
	v_cvt_pk_bf16_f32 v3, v46, v47
	ds_write_b64 v213, v[2:3] offset:8768
	v_mul_f32_e32 v48, v48, v218
	v_mul_f32_e32 v49, v49, v218
	v_mul_f32_e32 v50, v50, v218
	v_mul_f32_e32 v51, v51, v218
	v_cvt_pk_bf16_f32 v214, v48, v49
	v_cvt_pk_bf16_f32 v215, v50, v51
	ds_write_b64 v213, v[214:215] offset:8800
	v_mul_f32_e32 v52, v52, v219
	v_mul_f32_e32 v53, v53, v219
	v_mul_f32_e32 v54, v54, v219
	v_mul_f32_e32 v55, v55, v219
	v_cvt_pk_bf16_f32 v2, v52, v53
	v_cvt_pk_bf16_f32 v3, v54, v55
	ds_write_b64 v213, v[2:3] offset:13056
	v_mul_f32_e32 v56, v56, v219
	v_mul_f32_e32 v57, v57, v219
	v_mul_f32_e32 v58, v58, v219
	v_mul_f32_e32 v59, v59, v219
	v_cvt_pk_bf16_f32 v214, v56, v57
	v_cvt_pk_bf16_f32 v215, v58, v59
	ds_write_b64 v213, v[214:215] offset:13088
	v_mul_f32_e32 v60, v60, v219
	v_mul_f32_e32 v61, v61, v219
	v_mul_f32_e32 v62, v62, v219
	v_mul_f32_e32 v63, v63, v219
	v_cvt_pk_bf16_f32 v2, v60, v61
	v_cvt_pk_bf16_f32 v3, v62, v63
	ds_write_b64 v213, v[2:3] offset:13120
	v_mul_f32_e32 v72, v72, v219
	v_mul_f32_e32 v73, v73, v219
	v_mul_f32_e32 v74, v74, v219
	v_mul_f32_e32 v75, v75, v219
	v_cvt_pk_bf16_f32 v214, v72, v73
	v_cvt_pk_bf16_f32 v215, v74, v75
	ds_write_b64 v213, v[214:215] offset:13152
	s_waitcnt lgkmcnt(0)
	s_barrier
	ds_read_b128 v[216:219], v143 offset:0
	ds_read_b128 v[228:231], v143 offset:4352
	ds_read_b128 v[232:235], v143 offset:8704
	ds_read_b128 v[236:239], v143 offset:13056
	ds_read_b128 v[240:243], v143 offset:17408
	ds_read_b128 v[244:247], v143 offset:21760
	ds_read_b128 v[248:251], v143 offset:26112
	ds_read_b128 v[252:255], v143 offset:30464
	v_mov_b32_e32 v220, v71
	s_waitcnt lgkmcnt(7)
	global_store_dwordx4 v220, v[216:219], s[46:47]
	v_add_u32_e32 v220, 0xc00, v220
	s_waitcnt lgkmcnt(6)
	global_store_dwordx4 v220, v[228:231], s[46:47]
	v_add_u32_e32 v220, 0xc00, v220
	s_waitcnt lgkmcnt(5)
	global_store_dwordx4 v220, v[232:235], s[46:47]
	v_add_u32_e32 v220, 0xc00, v220
	s_waitcnt lgkmcnt(4)
	global_store_dwordx4 v220, v[236:239], s[46:47]
	v_add_u32_e32 v220, 0xc00, v220
	s_waitcnt lgkmcnt(3)
	global_store_dwordx4 v220, v[240:243], s[46:47]
	v_add_u32_e32 v220, 0xc00, v220
	s_waitcnt lgkmcnt(2)
	global_store_dwordx4 v220, v[244:247], s[46:47]
	v_add_u32_e32 v220, 0xc00, v220
	s_waitcnt lgkmcnt(1)
	global_store_dwordx4 v220, v[248:251], s[46:47]
	v_add_u32_e32 v220, 0xc00, v220
	s_waitcnt lgkmcnt(0)
	global_store_dwordx4 v220, v[252:255], s[46:47]
	s_barrier
	s_add_u32 s46, s48, 0x1349c000
	s_addc_u32 s47, s49, 0
	s_add_u32 s46, s46, s18
	s_addc_u32 s47, s47, 0
	s_add_u32 s46, s46, 0x318000
	s_addc_u32 s47, s47, 0
	ds_read_b32 v216, v227 offset:0
	ds_read_b32 v217, v227 offset:64
	ds_read_b32 v218, v227 offset:128
	ds_read_b32 v219, v227 offset:192
	s_waitcnt lgkmcnt(0)
	v_mul_f32_e32 v76, v76, v216
	v_mul_f32_e32 v77, v77, v216
	v_mul_f32_e32 v78, v78, v216
	v_mul_f32_e32 v79, v79, v216
	v_cvt_pk_bf16_f32 v2, v76, v77
	v_cvt_pk_bf16_f32 v3, v78, v79
	ds_write_b64 v213, v[2:3] offset:0
	v_mul_f32_e32 v80, v80, v216
	v_mul_f32_e32 v81, v81, v216
	v_mul_f32_e32 v82, v82, v216
	v_mul_f32_e32 v83, v83, v216
	v_cvt_pk_bf16_f32 v214, v80, v81
	v_cvt_pk_bf16_f32 v215, v82, v83
	ds_write_b64 v213, v[214:215] offset:32
	v_mul_f32_e32 v84, v84, v216
	v_mul_f32_e32 v85, v85, v216
	v_mul_f32_e32 v86, v86, v216
	v_mul_f32_e32 v87, v87, v216
	v_cvt_pk_bf16_f32 v2, v84, v85
	v_cvt_pk_bf16_f32 v3, v86, v87
	ds_write_b64 v213, v[2:3] offset:64
	v_mul_f32_e32 v144, v144, v216
	v_mul_f32_e32 v145, v145, v216
	v_mul_f32_e32 v146, v146, v216
	v_mul_f32_e32 v147, v147, v216
	v_cvt_pk_bf16_f32 v214, v144, v145
	v_cvt_pk_bf16_f32 v215, v146, v147
	ds_write_b64 v213, v[214:215] offset:96
	v_mul_f32_e32 v148, v148, v217
	v_mul_f32_e32 v149, v149, v217
	v_mul_f32_e32 v150, v150, v217
	v_mul_f32_e32 v151, v151, v217
	v_cvt_pk_bf16_f32 v2, v148, v149
	v_cvt_pk_bf16_f32 v3, v150, v151
	ds_write_b64 v213, v[2:3] offset:4352
	v_mul_f32_e32 v152, v152, v217
	v_mul_f32_e32 v153, v153, v217
	v_mul_f32_e32 v154, v154, v217
	v_mul_f32_e32 v155, v155, v217
	v_cvt_pk_bf16_f32 v214, v152, v153
	v_cvt_pk_bf16_f32 v215, v154, v155
	ds_write_b64 v213, v[214:215] offset:4384
	v_mul_f32_e32 v156, v156, v217
	v_mul_f32_e32 v157, v157, v217
	v_mul_f32_e32 v158, v158, v217
	v_mul_f32_e32 v159, v159, v217
	v_cvt_pk_bf16_f32 v2, v156, v157
	v_cvt_pk_bf16_f32 v3, v158, v159
	ds_write_b64 v213, v[2:3] offset:4416
	v_mul_f32_e32 v160, v160, v217
	v_mul_f32_e32 v161, v161, v217
	v_mul_f32_e32 v162, v162, v217
	v_mul_f32_e32 v163, v163, v217
	v_cvt_pk_bf16_f32 v214, v160, v161
	v_cvt_pk_bf16_f32 v215, v162, v163
	ds_write_b64 v213, v[214:215] offset:4448
	v_mul_f32_e32 v164, v164, v218
	v_mul_f32_e32 v165, v165, v218
	v_mul_f32_e32 v166, v166, v218
	v_mul_f32_e32 v167, v167, v218
	v_cvt_pk_bf16_f32 v2, v164, v165
	v_cvt_pk_bf16_f32 v3, v166, v167
	ds_write_b64 v213, v[2:3] offset:8704
	v_mul_f32_e32 v168, v168, v218
	v_mul_f32_e32 v169, v169, v218
	v_mul_f32_e32 v170, v170, v218
	v_mul_f32_e32 v171, v171, v218
	v_cvt_pk_bf16_f32 v214, v168, v169
	v_cvt_pk_bf16_f32 v215, v170, v171
	ds_write_b64 v213, v[214:215] offset:8736
	v_mul_f32_e32 v172, v172, v218
	v_mul_f32_e32 v173, v173, v218
	v_mul_f32_e32 v174, v174, v218
	v_mul_f32_e32 v175, v175, v218
	v_cvt_pk_bf16_f32 v2, v172, v173
	v_cvt_pk_bf16_f32 v3, v174, v175
	ds_write_b64 v213, v[2:3] offset:8768
	v_mul_f32_e32 v176, v176, v218
	v_mul_f32_e32 v177, v177, v218
	v_mul_f32_e32 v178, v178, v218
	v_mul_f32_e32 v179, v179, v218
	v_cvt_pk_bf16_f32 v214, v176, v177
	v_cvt_pk_bf16_f32 v215, v178, v179
	ds_write_b64 v213, v[214:215] offset:8800
	v_mul_f32_e32 v180, v180, v219
	v_mul_f32_e32 v181, v181, v219
	v_mul_f32_e32 v182, v182, v219
	v_mul_f32_e32 v183, v183, v219
	v_cvt_pk_bf16_f32 v2, v180, v181
	v_cvt_pk_bf16_f32 v3, v182, v183
	ds_write_b64 v213, v[2:3] offset:13056
	v_mul_f32_e32 v184, v184, v219
	v_mul_f32_e32 v185, v185, v219
	v_mul_f32_e32 v186, v186, v219
	v_mul_f32_e32 v187, v187, v219
	v_cvt_pk_bf16_f32 v214, v184, v185
	v_cvt_pk_bf16_f32 v215, v186, v187
	ds_write_b64 v213, v[214:215] offset:13088
	v_mul_f32_e32 v188, v188, v219
	v_mul_f32_e32 v189, v189, v219
	v_mul_f32_e32 v190, v190, v219
	v_mul_f32_e32 v191, v191, v219
	v_cvt_pk_bf16_f32 v2, v188, v189
	v_cvt_pk_bf16_f32 v3, v190, v191
	ds_write_b64 v213, v[2:3] offset:13120
	v_mul_f32_e32 v192, v192, v219
	v_mul_f32_e32 v193, v193, v219
	v_mul_f32_e32 v194, v194, v219
	v_mul_f32_e32 v195, v195, v219
	v_cvt_pk_bf16_f32 v214, v192, v193
	v_cvt_pk_bf16_f32 v215, v194, v195
	ds_write_b64 v213, v[214:215] offset:13152
	s_waitcnt lgkmcnt(0)
	s_barrier
	ds_read_b128 v[216:219], v143 offset:0
	ds_read_b128 v[228:231], v143 offset:4352
	ds_read_b128 v[232:235], v143 offset:8704
	ds_read_b128 v[236:239], v143 offset:13056
	ds_read_b128 v[240:243], v143 offset:17408
	ds_read_b128 v[244:247], v143 offset:21760
	ds_read_b128 v[248:251], v143 offset:26112
	ds_read_b128 v[252:255], v143 offset:30464
	v_mov_b32_e32 v220, v71
	s_waitcnt lgkmcnt(7)
	global_store_dwordx4 v220, v[216:219], s[46:47]
	v_add_u32_e32 v220, 0xc00, v220
	s_waitcnt lgkmcnt(6)
	global_store_dwordx4 v220, v[228:231], s[46:47]
	v_add_u32_e32 v220, 0xc00, v220
	s_waitcnt lgkmcnt(5)
	global_store_dwordx4 v220, v[232:235], s[46:47]
	v_add_u32_e32 v220, 0xc00, v220
	s_waitcnt lgkmcnt(4)
	global_store_dwordx4 v220, v[236:239], s[46:47]
	v_add_u32_e32 v220, 0xc00, v220
	s_waitcnt lgkmcnt(3)
	global_store_dwordx4 v220, v[240:243], s[46:47]
	v_add_u32_e32 v220, 0xc00, v220
	s_waitcnt lgkmcnt(2)
	global_store_dwordx4 v220, v[244:247], s[46:47]
	v_add_u32_e32 v220, 0xc00, v220
	s_waitcnt lgkmcnt(1)
	global_store_dwordx4 v220, v[248:251], s[46:47]
	v_add_u32_e32 v220, 0xc00, v220
	s_waitcnt lgkmcnt(0)
	global_store_dwordx4 v220, v[252:255], s[46:47]
	s_barrier
	s_branch .LBB0_314
.Lukv_v:
	s_mov_b32 s17, 0
	s_mov_b32 s36, 0
	s_mov_b32 s37, 0xc000

.Lukv_nofillv:
	v_add_u32_e32 v220, s36, v64
	v_add_u32_e32 v227, s36, v65
	ds_read_b128 v[216:219], v220
	ds_read_b128 v[228:231], v220 offset:1024
	ds_read_b128 v[232:235], v220 offset:2048
	ds_read_b128 v[236:239], v220 offset:3072
	ds_read_b128 v[240:243], v227 offset:8192
	ds_read_b128 v[244:247], v227 offset:9216
	ds_read_b128 v[248:251], v227 offset:10240
	ds_read_b128 v[252:255], v227 offset:11264
	s_waitcnt lgkmcnt(3)
	v_mfma_f32_16x16x32_bf16 v[4:7], v[216:219], v[240:243], v[4:7]
	v_mfma_f32_16x16x32_bf16 v[20:23], v[228:231], v[240:243], v[20:23]
	v_mfma_f32_16x16x32_bf16 v[36:39], v[232:235], v[240:243], v[36:39]
	v_mfma_f32_16x16x32_bf16 v[52:55], v[236:239], v[240:243], v[52:55]
	ds_read_b128 v[240:243], v227 offset:16384
	s_waitcnt lgkmcnt(3)
	v_mfma_f32_16x16x32_bf16 v[8:11], v[216:219], v[244:247], v[8:11]
	v_mfma_f32_16x16x32_bf16 v[24:27], v[228:231], v[244:247], v[24:27]
	v_mfma_f32_16x16x32_bf16 v[40:43], v[232:235], v[244:247], v[40:43]
	v_mfma_f32_16x16x32_bf16 v[56:59], v[236:239], v[244:247], v[56:59]
	ds_read_b128 v[244:247], v227 offset:17408
	s_waitcnt lgkmcnt(3)
	v_mfma_f32_16x16x32_bf16 v[12:15], v[216:219], v[248:251], v[12:15]
	v_mfma_f32_16x16x32_bf16 v[28:31], v[228:231], v[248:251], v[28:31]
	v_mfma_f32_16x16x32_bf16 v[44:47], v[232:235], v[248:251], v[44:47]
	v_mfma_f32_16x16x32_bf16 v[60:63], v[236:239], v[248:251], v[60:63]
	ds_read_b128 v[248:251], v227 offset:18432
	s_waitcnt lgkmcnt(3)
	v_mfma_f32_16x16x32_bf16 v[16:19], v[216:219], v[252:255], v[16:19]
	v_mfma_f32_16x16x32_bf16 v[32:35], v[228:231], v[252:255], v[32:35]
	v_mfma_f32_16x16x32_bf16 v[48:51], v[232:235], v[252:255], v[48:51]
	v_mfma_f32_16x16x32_bf16 v[72:75], v[236:239], v[252:255], v[72:75]
	ds_read_b128 v[252:255], v227 offset:19456
	s_waitcnt lgkmcnt(3)
	v_mfma_f32_16x16x32_bf16 v[76:79], v[216:219], v[240:243], v[76:79]
	v_mfma_f32_16x16x32_bf16 v[148:151], v[228:231], v[240:243], v[148:151]
	v_mfma_f32_16x16x32_bf16 v[164:167], v[232:235], v[240:243], v[164:167]
	v_mfma_f32_16x16x32_bf16 v[180:183], v[236:239], v[240:243], v[180:183]
	s_waitcnt lgkmcnt(2)
	v_mfma_f32_16x16x32_bf16 v[80:83], v[216:219], v[244:247], v[80:83]
	v_mfma_f32_16x16x32_bf16 v[152:155], v[228:231], v[244:247], v[152:155]
	v_mfma_f32_16x16x32_bf16 v[168:171], v[232:235], v[244:247], v[168:171]
	v_mfma_f32_16x16x32_bf16 v[184:187], v[236:239], v[244:247], v[184:187]
	s_waitcnt lgkmcnt(1)
	v_mfma_f32_16x16x32_bf16 v[84:87], v[216:219], v[248:251], v[84:87]
	v_mfma_f32_16x16x32_bf16 v[156:159], v[228:231], v[248:251], v[156:159]
	v_mfma_f32_16x16x32_bf16 v[172:175], v[232:235], v[248:251], v[172:175]
	v_mfma_f32_16x16x32_bf16 v[188:191], v[236:239], v[248:251], v[188:191]
	s_waitcnt lgkmcnt(0)
	v_mfma_f32_16x16x32_bf16 v[144:147], v[216:219], v[252:255], v[144:147]
	v_mfma_f32_16x16x32_bf16 v[160:163], v[228:231], v[252:255], v[160:163]
	v_mfma_f32_16x16x32_bf16 v[176:179], v[232:235], v[252:255], v[176:179]
	v_mfma_f32_16x16x32_bf16 v[192:195], v[236:239], v[252:255], v[192:195]
	s_add_i32 s36, s36, 0x6000
	s_cmp_eq_u32 s36, 0x12000
	s_cselect_b32 s36, 0, s36
	s_add_i32 s37, s37, 0x6000
	s_cmp_eq_u32 s37, 0x12000
	s_cselect_b32 s37, 0, s37
	s_add_i32 s17, s17, 1
	s_cmp_lt_u32 s17, 7
	s_cbranch_scc1 .Lukv_loopv
	s_waitcnt vmcnt(0)
	s_barrier
	v_add_u32_e32 v220, s36, v64
	v_add_u32_e32 v227, s36, v65
	ds_read_b128 v[216:219], v220
	ds_read_b128 v[228:231], v220 offset:1024
	ds_read_b128 v[232:235], v220 offset:2048
	ds_read_b128 v[236:239], v220 offset:3072
	ds_read_b128 v[240:243], v227 offset:8192
	ds_read_b128 v[244:247], v227 offset:9216
	ds_read_b128 v[248:251], v227 offset:10240
	ds_read_b128 v[252:255], v227 offset:11264
	s_waitcnt lgkmcnt(3)
	v_mfma_f32_16x16x32_bf16 v[4:7], v[216:219], v[240:243], v[4:7]
	v_mfma_f32_16x16x32_bf16 v[20:23], v[228:231], v[240:243], v[20:23]
	v_mfma_f32_16x16x32_bf16 v[36:39], v[232:235], v[240:243], v[36:39]
	v_mfma_f32_16x16x32_bf16 v[52:55], v[236:239], v[240:243], v[52:55]
	ds_read_b128 v[240:243], v227 offset:16384
	s_waitcnt lgkmcnt(3)
	v_mfma_f32_16x16x32_bf16 v[8:11], v[216:219], v[244:247], v[8:11]
	v_mfma_f32_16x16x32_bf16 v[24:27], v[228:231], v[244:247], v[24:27]
	v_mfma_f32_16x16x32_bf16 v[40:43], v[232:235], v[244:247], v[40:43]
	v_mfma_f32_16x16x32_bf16 v[56:59], v[236:239], v[244:247], v[56:59]
	ds_read_b128 v[244:247], v227 offset:17408
	s_waitcnt lgkmcnt(3)
	v_mfma_f32_16x16x32_bf16 v[12:15], v[216:219], v[248:251], v[12:15]
	v_mfma_f32_16x16x32_bf16 v[28:31], v[228:231], v[248:251], v[28:31]
	v_mfma_f32_16x16x32_bf16 v[44:47], v[232:235], v[248:251], v[44:47]
	v_mfma_f32_16x16x32_bf16 v[60:63], v[236:239], v[248:251], v[60:63]
	ds_read_b128 v[248:251], v227 offset:18432
	s_waitcnt lgkmcnt(3)
	v_mfma_f32_16x16x32_bf16 v[16:19], v[216:219], v[252:255], v[16:19]
	v_mfma_f32_16x16x32_bf16 v[32:35], v[228:231], v[252:255], v[32:35]
	v_mfma_f32_16x16x32_bf16 v[48:51], v[232:235], v[252:255], v[48:51]
	v_mfma_f32_16x16x32_bf16 v[72:75], v[236:239], v[252:255], v[72:75]
	ds_read_b128 v[252:255], v227 offset:19456
	s_waitcnt lgkmcnt(3)
	v_mfma_f32_16x16x32_bf16 v[76:79], v[216:219], v[240:243], v[76:79]
	v_mfma_f32_16x16x32_bf16 v[148:151], v[228:231], v[240:243], v[148:151]
	v_mfma_f32_16x16x32_bf16 v[164:167], v[232:235], v[240:243], v[164:167]
	v_mfma_f32_16x16x32_bf16 v[180:183], v[236:239], v[240:243], v[180:183]
	s_waitcnt lgkmcnt(2)
	v_mfma_f32_16x16x32_bf16 v[80:83], v[216:219], v[244:247], v[80:83]
	v_mfma_f32_16x16x32_bf16 v[152:155], v[228:231], v[244:247], v[152:155]
	v_mfma_f32_16x16x32_bf16 v[168:171], v[232:235], v[244:247], v[168:171]
	v_mfma_f32_16x16x32_bf16 v[184:187], v[236:239], v[244:247], v[184:187]
	s_waitcnt lgkmcnt(1)
	v_mfma_f32_16x16x32_bf16 v[84:87], v[216:219], v[248:251], v[84:87]
	v_mfma_f32_16x16x32_bf16 v[156:159], v[228:231], v[248:251], v[156:159]
	v_mfma_f32_16x16x32_bf16 v[172:175], v[232:235], v[248:251], v[172:175]
	v_mfma_f32_16x16x32_bf16 v[188:191], v[236:239], v[248:251], v[188:191]
	s_waitcnt lgkmcnt(0)
	v_mfma_f32_16x16x32_bf16 v[144:147], v[216:219], v[252:255], v[144:147]
	v_mfma_f32_16x16x32_bf16 v[160:163], v[228:231], v[252:255], v[160:163]
	v_mfma_f32_16x16x32_bf16 v[176:179], v[232:235], v[252:255], v[176:179]
	v_mfma_f32_16x16x32_bf16 v[192:195], v[236:239], v[252:255], v[192:195]
	s_barrier
	v_and_b32_e32 v213, 15, v196
	v_bfe_u32 v220, v196, 6, 1
	v_lshl_add_u32 v213, v220, 6, v213
	v_mul_u32_u24_e32 v213, 0x110, v213
	v_lshrrev_b32_e32 v220, 7, v196
	v_lshl_add_u32 v213, v220, 7, v213
	v_bfe_u32 v0, v196, 4, 2
	v_lshl_add_u32 v213, v0, 3, v213
	v_lshl_add_u32 v227, v220, 6, 0
	v_lshl_add_u32 v227, v0, 2, v227
	v_lshlrev_b32_e32 v227, 2, v227
	v_add_u32_e32 v227, 0x12000, v227
	v_lshrrev_b32_e32 v220, 4, v196
	v_and_b32_e32 v0, 15, v196
	v_lshlrev_b32_e32 v0, 4, v0
	v_mad_u32_u24 v143, v220, s30, v0
	s_movk_i32 s0, 0x4200
	v_mad_u32_u24 v71, v220, s0, v0
	s_add_u32 s46, s48, 0x1661c000
	s_addc_u32 s47, s49, 0
	s_add_u32 s46, s46, s18
	s_addc_u32 s47, s47, 0
	ds_read_b128 v[216:219], v227 offset:0
	ds_read_b128 v[228:231], v227 offset:64
	ds_read_b128 v[232:235], v227 offset:128
	ds_read_b128 v[236:239], v227 offset:192
	s_waitcnt lgkmcnt(0)
	v_mul_f32_e32 v4, v4, v216
	v_mul_f32_e32 v5, v5, v217
	v_mul_f32_e32 v6, v6, v218
	v_mul_f32_e32 v7, v7, v219
	v_cvt_pk_bf16_f32 v2, v4, v5
	v_cvt_pk_bf16_f32 v3, v6, v7
	ds_write_b64 v213, v[2:3] offset:0
	v_mul_f32_e32 v20, v20, v228
	v_mul_f32_e32 v21, v21, v229
	v_mul_f32_e32 v22, v22, v230
	v_mul_f32_e32 v23, v23, v231
	v_cvt_pk_bf16_f32 v214, v20, v21
	v_cvt_pk_bf16_f32 v215, v22, v23
	ds_write_b64 v213, v[214:215] offset:32
	v_mul_f32_e32 v36, v36, v232
	v_mul_f32_e32 v37, v37, v233
	v_mul_f32_e32 v38, v38, v234
	v_mul_f32_e32 v39, v39, v235
	v_cvt_pk_bf16_f32 v2, v36, v37
	v_cvt_pk_bf16_f32 v3, v38, v39
	ds_write_b64 v213, v[2:3] offset:64
	v_mul_f32_e32 v52, v52, v236
	v_mul_f32_e32 v53, v53, v237
	v_mul_f32_e32 v54, v54, v238
	v_mul_f32_e32 v55, v55, v239
	v_cvt_pk_bf16_f32 v214, v52, v53
	v_cvt_pk_bf16_f32 v215, v54, v55
	ds_write_b64 v213, v[214:215] offset:96
	v_mul_f32_e32 v8, v8, v216
	v_mul_f32_e32 v9, v9, v217
	v_mul_f32_e32 v10, v10, v218
	v_mul_f32_e32 v11, v11, v219
	v_cvt_pk_bf16_f32 v2, v8, v9
	v_cvt_pk_bf16_f32 v3, v10, v11
	ds_write_b64 v213, v[2:3] offset:4352
	v_mul_f32_e32 v24, v24, v228
	v_mul_f32_e32 v25, v25, v229
	v_mul_f32_e32 v26, v26, v230
	v_mul_f32_e32 v27, v27, v231
	v_cvt_pk_bf16_f32 v214, v24, v25
	v_cvt_pk_bf16_f32 v215, v26, v27
	ds_write_b64 v213, v[214:215] offset:4384
	v_mul_f32_e32 v40, v40, v232
	v_mul_f32_e32 v41, v41, v233
	v_mul_f32_e32 v42, v42, v234
	v_mul_f32_e32 v43, v43, v235
	v_cvt_pk_bf16_f32 v2, v40, v41
	v_cvt_pk_bf16_f32 v3, v42, v43
	ds_write_b64 v213, v[2:3] offset:4416
	v_mul_f32_e32 v56, v56, v236
	v_mul_f32_e32 v57, v57, v237
	v_mul_f32_e32 v58, v58, v238
	v_mul_f32_e32 v59, v59, v239
	v_cvt_pk_bf16_f32 v214, v56, v57
	v_cvt_pk_bf16_f32 v215, v58, v59
	ds_write_b64 v213, v[214:215] offset:4448
	v_mul_f32_e32 v12, v12, v216
	v_mul_f32_e32 v13, v13, v217
	v_mul_f32_e32 v14, v14, v218
	v_mul_f32_e32 v15, v15, v219
	v_cvt_pk_bf16_f32 v2, v12, v13
	v_cvt_pk_bf16_f32 v3, v14, v15
	ds_write_b64 v213, v[2:3] offset:8704
	v_mul_f32_e32 v28, v28, v228
	v_mul_f32_e32 v29, v29, v229
	v_mul_f32_e32 v30, v30, v230
	v_mul_f32_e32 v31, v31, v231
	v_cvt_pk_bf16_f32 v214, v28, v29
	v_cvt_pk_bf16_f32 v215, v30, v31
	ds_write_b64 v213, v[214:215] offset:8736
	v_mul_f32_e32 v44, v44, v232
	v_mul_f32_e32 v45, v45, v233
	v_mul_f32_e32 v46, v46, v234
	v_mul_f32_e32 v47, v47, v235
	v_cvt_pk_bf16_f32 v2, v44, v45
	v_cvt_pk_bf16_f32 v3, v46, v47
	ds_write_b64 v213, v[2:3] offset:8768
	v_mul_f32_e32 v60, v60, v236
	v_mul_f32_e32 v61, v61, v237
	v_mul_f32_e32 v62, v62, v238
	v_mul_f32_e32 v63, v63, v239
	v_cvt_pk_bf16_f32 v214, v60, v61
	v_cvt_pk_bf16_f32 v215, v62, v63
	ds_write_b64 v213, v[214:215] offset:8800
	v_mul_f32_e32 v16, v16, v216
	v_mul_f32_e32 v17, v17, v217
	v_mul_f32_e32 v18, v18, v218
	v_mul_f32_e32 v19, v19, v219
	v_cvt_pk_bf16_f32 v2, v16, v17
	v_cvt_pk_bf16_f32 v3, v18, v19
	ds_write_b64 v213, v[2:3] offset:13056
	v_mul_f32_e32 v32, v32, v228
	v_mul_f32_e32 v33, v33, v229
	v_mul_f32_e32 v34, v34, v230
	v_mul_f32_e32 v35, v35, v231
	v_cvt_pk_bf16_f32 v214, v32, v33
	v_cvt_pk_bf16_f32 v215, v34, v35
	ds_write_b64 v213, v[214:215] offset:13088
	v_mul_f32_e32 v48, v48, v232
	v_mul_f32_e32 v49, v49, v233
	v_mul_f32_e32 v50, v50, v234
	v_mul_f32_e32 v51, v51, v235
	v_cvt_pk_bf16_f32 v2, v48, v49
	v_cvt_pk_bf16_f32 v3, v50, v51
	ds_write_b64 v213, v[2:3] offset:13120
	v_mul_f32_e32 v72, v72, v236
	v_mul_f32_e32 v73, v73, v237
	v_mul_f32_e32 v74, v74, v238
	v_mul_f32_e32 v75, v75, v239
	v_cvt_pk_bf16_f32 v214, v72, v73
	v_cvt_pk_bf16_f32 v215, v74, v75
	ds_write_b64 v213, v[214:215] offset:13152
	s_waitcnt lgkmcnt(0)
	s_barrier
	ds_read_b128 v[216:219], v143 offset:0
	ds_read_b128 v[228:231], v143 offset:4352
	ds_read_b128 v[232:235], v143 offset:8704
	ds_read_b128 v[236:239], v143 offset:13056
	ds_read_b128 v[240:243], v143 offset:17408
	ds_read_b128 v[244:247], v143 offset:21760
	ds_read_b128 v[248:251], v143 offset:26112
	ds_read_b128 v[252:255], v143 offset:30464
	v_mov_b32_e32 v220, v71
	s_waitcnt lgkmcnt(7)
	global_store_dwordx4 v220, v[216:219], s[46:47]
	v_add_u32_e32 v220, 0x42000, v220
	s_waitcnt lgkmcnt(6)
	global_store_dwordx4 v220, v[228:231], s[46:47]
	v_add_u32_e32 v220, 0x42000, v220
	s_waitcnt lgkmcnt(5)
	global_store_dwordx4 v220, v[232:235], s[46:47]
	v_add_u32_e32 v220, 0x42000, v220
	s_waitcnt lgkmcnt(4)
	global_store_dwordx4 v220, v[236:239], s[46:47]
	v_add_u32_e32 v220, 0x42000, v220
	s_waitcnt lgkmcnt(3)
	global_store_dwordx4 v220, v[240:243], s[46:47]
	v_add_u32_e32 v220, 0x42000, v220
	s_waitcnt lgkmcnt(2)
	global_store_dwordx4 v220, v[244:247], s[46:47]
	v_add_u32_e32 v220, 0x42000, v220
	s_waitcnt lgkmcnt(1)
	global_store_dwordx4 v220, v[248:251], s[46:47]
	v_add_u32_e32 v220, 0x42000, v220
	s_waitcnt lgkmcnt(0)
	global_store_dwordx4 v220, v[252:255], s[46:47]
	s_barrier
	s_add_u32 s46, s48, 0x1661c000
	s_addc_u32 s47, s49, 0
	s_add_u32 s46, s46, s18
	s_addc_u32 s47, s47, 0
	s_add_u32 s46, s46, 0x210000
	s_addc_u32 s47, s47, 0
	ds_read_b128 v[216:219], v227 offset:0
	ds_read_b128 v[228:231], v227 offset:64
	ds_read_b128 v[232:235], v227 offset:128
	ds_read_b128 v[236:239], v227 offset:192
	s_waitcnt lgkmcnt(0)
	v_mul_f32_e32 v76, v76, v216
	v_mul_f32_e32 v77, v77, v217
	v_mul_f32_e32 v78, v78, v218
	v_mul_f32_e32 v79, v79, v219
	v_cvt_pk_bf16_f32 v2, v76, v77
	v_cvt_pk_bf16_f32 v3, v78, v79
	ds_write_b64 v213, v[2:3] offset:0
	v_mul_f32_e32 v148, v148, v228
	v_mul_f32_e32 v149, v149, v229
	v_mul_f32_e32 v150, v150, v230
	v_mul_f32_e32 v151, v151, v231
	v_cvt_pk_bf16_f32 v214, v148, v149
	v_cvt_pk_bf16_f32 v215, v150, v151
	ds_write_b64 v213, v[214:215] offset:32
	v_mul_f32_e32 v164, v164, v232
	v_mul_f32_e32 v165, v165, v233
	v_mul_f32_e32 v166, v166, v234
	v_mul_f32_e32 v167, v167, v235
	v_cvt_pk_bf16_f32 v2, v164, v165
	v_cvt_pk_bf16_f32 v3, v166, v167
	ds_write_b64 v213, v[2:3] offset:64
	v_mul_f32_e32 v180, v180, v236
	v_mul_f32_e32 v181, v181, v237
	v_mul_f32_e32 v182, v182, v238
	v_mul_f32_e32 v183, v183, v239
	v_cvt_pk_bf16_f32 v214, v180, v181
	v_cvt_pk_bf16_f32 v215, v182, v183
	ds_write_b64 v213, v[214:215] offset:96
	v_mul_f32_e32 v80, v80, v216
	v_mul_f32_e32 v81, v81, v217
	v_mul_f32_e32 v82, v82, v218
	v_mul_f32_e32 v83, v83, v219
	v_cvt_pk_bf16_f32 v2, v80, v81
	v_cvt_pk_bf16_f32 v3, v82, v83
	ds_write_b64 v213, v[2:3] offset:4352
	v_mul_f32_e32 v152, v152, v228
	v_mul_f32_e32 v153, v153, v229
	v_mul_f32_e32 v154, v154, v230
	v_mul_f32_e32 v155, v155, v231
	v_cvt_pk_bf16_f32 v214, v152, v153
	v_cvt_pk_bf16_f32 v215, v154, v155
	ds_write_b64 v213, v[214:215] offset:4384
	v_mul_f32_e32 v168, v168, v232
	v_mul_f32_e32 v169, v169, v233
	v_mul_f32_e32 v170, v170, v234
	v_mul_f32_e32 v171, v171, v235
	v_cvt_pk_bf16_f32 v2, v168, v169
	v_cvt_pk_bf16_f32 v3, v170, v171
	ds_write_b64 v213, v[2:3] offset:4416
	v_mul_f32_e32 v184, v184, v236
	v_mul_f32_e32 v185, v185, v237
	v_mul_f32_e32 v186, v186, v238
	v_mul_f32_e32 v187, v187, v239
	v_cvt_pk_bf16_f32 v214, v184, v185
	v_cvt_pk_bf16_f32 v215, v186, v187
	ds_write_b64 v213, v[214:215] offset:4448
	v_mul_f32_e32 v84, v84, v216
	v_mul_f32_e32 v85, v85, v217
	v_mul_f32_e32 v86, v86, v218
	v_mul_f32_e32 v87, v87, v219
	v_cvt_pk_bf16_f32 v2, v84, v85
	v_cvt_pk_bf16_f32 v3, v86, v87
	ds_write_b64 v213, v[2:3] offset:8704
	v_mul_f32_e32 v156, v156, v228
	v_mul_f32_e32 v157, v157, v229
	v_mul_f32_e32 v158, v158, v230
	v_mul_f32_e32 v159, v159, v231
	v_cvt_pk_bf16_f32 v214, v156, v157
	v_cvt_pk_bf16_f32 v215, v158, v159
	ds_write_b64 v213, v[214:215] offset:8736
	v_mul_f32_e32 v172, v172, v232
	v_mul_f32_e32 v173, v173, v233
	v_mul_f32_e32 v174, v174, v234
	v_mul_f32_e32 v175, v175, v235
	v_cvt_pk_bf16_f32 v2, v172, v173
	v_cvt_pk_bf16_f32 v3, v174, v175
	ds_write_b64 v213, v[2:3] offset:8768
	v_mul_f32_e32 v188, v188, v236
	v_mul_f32_e32 v189, v189, v237
	v_mul_f32_e32 v190, v190, v238
	v_mul_f32_e32 v191, v191, v239
	v_cvt_pk_bf16_f32 v214, v188, v189
	v_cvt_pk_bf16_f32 v215, v190, v191
	ds_write_b64 v213, v[214:215] offset:8800
	v_mul_f32_e32 v144, v144, v216
	v_mul_f32_e32 v145, v145, v217
	v_mul_f32_e32 v146, v146, v218
	v_mul_f32_e32 v147, v147, v219
	v_cvt_pk_bf16_f32 v2, v144, v145
	v_cvt_pk_bf16_f32 v3, v146, v147
	ds_write_b64 v213, v[2:3] offset:13056
	v_mul_f32_e32 v160, v160, v228
	v_mul_f32_e32 v161, v161, v229
	v_mul_f32_e32 v162, v162, v230
	v_mul_f32_e32 v163, v163, v231
	v_cvt_pk_bf16_f32 v214, v160, v161
	v_cvt_pk_bf16_f32 v215, v162, v163
	ds_write_b64 v213, v[214:215] offset:13088
	v_mul_f32_e32 v176, v176, v232
	v_mul_f32_e32 v177, v177, v233
	v_mul_f32_e32 v178, v178, v234
	v_mul_f32_e32 v179, v179, v235
	v_cvt_pk_bf16_f32 v2, v176, v177
	v_cvt_pk_bf16_f32 v3, v178, v179
	ds_write_b64 v213, v[2:3] offset:13120
	v_mul_f32_e32 v192, v192, v236
	v_mul_f32_e32 v193, v193, v237
	v_mul_f32_e32 v194, v194, v238
	v_mul_f32_e32 v195, v195, v239
	v_cvt_pk_bf16_f32 v214, v192, v193
	v_cvt_pk_bf16_f32 v215, v194, v195
	ds_write_b64 v213, v[214:215] offset:13152
	s_waitcnt lgkmcnt(0)
	s_barrier
	ds_read_b128 v[216:219], v143 offset:0
	ds_read_b128 v[228:231], v143 offset:4352
	ds_read_b128 v[232:235], v143 offset:8704
	ds_read_b128 v[236:239], v143 offset:13056
	ds_read_b128 v[240:243], v143 offset:17408
	ds_read_b128 v[244:247], v143 offset:21760
	ds_read_b128 v[248:251], v143 offset:26112
	ds_read_b128 v[252:255], v143 offset:30464
	v_mov_b32_e32 v220, v71
	s_waitcnt lgkmcnt(7)
	global_store_dwordx4 v220, v[216:219], s[46:47]
	v_add_u32_e32 v220, 0x42000, v220
	s_waitcnt lgkmcnt(6)
	global_store_dwordx4 v220, v[228:231], s[46:47]
	v_add_u32_e32 v220, 0x42000, v220
	s_waitcnt lgkmcnt(5)
	global_store_dwordx4 v220, v[232:235], s[46:47]
	v_add_u32_e32 v220, 0x42000, v220
	s_waitcnt lgkmcnt(4)
	global_store_dwordx4 v220, v[236:239], s[46:47]
	v_add_u32_e32 v220, 0x42000, v220
	s_waitcnt lgkmcnt(3)
	global_store_dwordx4 v220, v[240:243], s[46:47]
	v_add_u32_e32 v220, 0x42000, v220
	s_waitcnt lgkmcnt(2)
	global_store_dwordx4 v220, v[244:247], s[46:47]
	v_add_u32_e32 v220, 0x42000, v220
	s_waitcnt lgkmcnt(1)
	global_store_dwordx4 v220, v[248:251], s[46:47]
	v_add_u32_e32 v220, 0x42000, v220
	s_waitcnt lgkmcnt(0)
	global_store_dwordx4 v220, v[252:255], s[46:47]
	s_barrier
	s_branch .LBB0_314
